# idlew2 + proidle: layer-1 FFN1 weights also converted in layer-0 FFN2-up idle slots
# baseline (speedup 1.0000x reference)
; __device__ __forceinline__ void prologue(Frame& F, const Args& A, int l) {
;     ...
;     for (int it = gw; it < NITEMS; it += NGW) {
;         int r = it, si, sci = -1, K = DM, N = FFH, rs = 128, off = 0, nblk = 32; size_t so = oFF, dsto;
;         if (r < 6 * 1408) { const int w = r / 1408; r -= w * 1408; const int second = w >= 3, t = w % 3;
;             if (t < 2) { si = (second ? 19 : 3) + t; sci = second ? 18 : 2; rs = 256; off = 128 * t; nblk = 88; dsto = second ? WS_W2A : WS_W1A; }
;             else { si = second ? 21 : 5; K = FFH; N = DM; dsto = second ? WS_W2B : WS_W1B; } }
.Lpi_b11:
	s_cmpk_lt_i32 s13, 0x1080
	s_cbranch_scc1 .Lpi_Lpro_keepw2
	s_cmpk_gt_i32 s13, 0x20ff
	s_cbranch_scc1 .Lpi_Lpro_keepw2
	s_add_i32 s13, s13, s12
	s_cmpk_gt_i32 s13, 0x107f
	s_cbranch_scc1 .Lpi_exit
	s_branch .Lpi_b11
